# LDS bank-conflict swizzle of the attention K and V^T tile images (granule bit0 xor for rows 4-11), producer epilogues and consumer addresses
# speedup vs baseline: 1.0086x; 1.0057x over previous
.LBB0_106:
	s_lshl_b32 s3, s3, 5
	s_and_b32 s3, s3, 0x60
	s_add_i32 m0, s37, 0x18000
	v_lshl_add_u64 v[8:9], v[8:9], 0, s[64:65]
	s_lshl_b32 s45, s4, 6
	s_lshl_b32 s18, s4, 13
	s_lshl_b32 s19, s3, 7
	s_waitcnt vmcnt(2)
	s_barrier
	global_load_lds_dwordx4 v[8:9], off
	v_lshl_add_u64 v[6:7], v[6:7], 0, s[64:65]
	s_add_i32 m0, s37, 0x1a000
	s_add_i32 s46, s37, 0x8000
	s_add_i32 s47, s37, 0xa000
	global_load_lds_dwordx4 v[6:7], off
	v_lshl_add_u64 v[2:3], v[2:3], 0, s[64:65]
	s_mov_b32 m0, s46
	s_add_u32 s4, s30, 0x80080
	global_load_lds_dwordx4 v[2:3], off
	v_lshl_add_u64 v[2:3], v[4:5], 0, s[64:65]
	s_mov_b32 m0, s47
	s_addc_u32 s5, s31, 0
	global_load_lds_dwordx4 v[2:3], off
	s_add_i32 m0, s37, 0x1c000
	v_lshl_add_u64 v[2:3], s[4:5], 0, v[166:167]
	global_load_lds_dwordx4 v[2:3], off
	v_lshl_add_u64 v[2:3], s[4:5], 0, v[162:163]
	s_add_i32 m0, s37, 0x1e000
	v_and_b32_e32 v171, 15, v177
	global_load_lds_dwordx4 v[2:3], off
	v_lshrrev_b32_e32 v2, 1, v177
	v_and_b32_e32 v2, 24, v2
	v_lshlrev_b32_e32 v3, 1, v2
	v_lshlrev_b32_e32 v4, 2, v177
	v_or_b32_e32 v170, s3, v2
	v_mul_u32_u24_e32 v2, 0x88, v171
	v_lshl_or_b32 v3, v171, 6, v3
	v_and_b32_e32 v4, 32, v4
	v_lshlrev_b32_e32 v210, 1, v2
	v_bitop3_b32 v5, v3, s18, v4 bitop3:0xde
	v_bitop3_b32 v240, v3, s19, v4 bitop3:0xde
	v_lshl_add_u64 v[2:3], s[20:21], 0, v[210:211]
	v_lshl_add_u64 v[172:173], v[2:3], 0, s[70:71]
	v_add_u32_e32 v2, 4, v177
	v_and_b32_e32 v2, 8, v2
	v_lshlrev_b32_e32 v2, 1, v2
	v_bfe_u32 v3, v177, 4, 1
	v_lshlrev_b32_e32 v3, 1, v3
	v_sub_u32_e32 v3, 1, v3
	v_mul_i32_i24_e32 v2, v2, v3
	v_ashrrev_i32_e32 v3, 31, v2
	v_lshl_add_u64 v[172:173], v[172:173], 0, v[2:3]
	v_lshlrev_b32_e32 v2, 15, v14
	v_and_b32_e32 v2, 0xffff0000, v2
	v_lshl_add_u32 v2, v13, 12, v2
	v_and_b32_e32 v3, 1, v14
	v_lshl_or_b32 v2, v3, 6, v2
	v_lshlrev_b32_e32 v210, 1, v170
	v_lshl_add_u32 v182, v15, 1, v2
	v_lshlrev_b32_e32 v2, 15, v10
	s_cmpk_lt_u32 s2, 0x100
	v_lshl_add_u64 v[174:175], v[172:173], 0, v[210:211]
	s_mov_b64 s[2:3], 0x1100
	v_and_b32_e32 v2, 0xffff0000, v2
	s_waitcnt vmcnt(6)
	v_lshl_add_u64 v[176:177], v[174:175], 0, s[2:3]
	s_mov_b64 s[2:3], 0x2200
	v_lshl_add_u32 v2, v11, 12, v2
	v_and_b32_e32 v3, 1, v10
	v_lshl_add_u64 v[178:179], v[174:175], 0, s[2:3]
	s_mov_b64 s[2:3], 0x3300
	v_lshl_or_b32 v2, v3, 6, v2
	v_readlane_b32 s4, v254, 0
	s_cselect_b64 s[18:19], -1, 0
	v_lshl_add_u64 v[180:181], v[174:175], 0, s[2:3]
	v_mov_b32_e32 v183, v211
	v_lshl_add_u32 v184, v12, 1, v2
	v_mov_b32_e32 v185, v211
	s_mov_b32 s48, 0
	v_add_u32_e32 v241, 0, v5
	v_readlane_b32 s2, v253, 21
	s_mov_b32 s3, s4
	s_barrier
	v_readlane_b32 s5, v254, 1
	s_branch .LBB0_109

.LBB0_259:
	s_andn2_b64 vcc, exec, s[2:3]
	s_cbranch_vccnz .LBB0_261
	v_lshlrev_b32_e32 v210, 1, v140
	v_lshl_add_u64 v[190:191], v[190:191], 0, v[210:211]
	v_lshlrev_b32_e32 v210, 1, v142
	v_lshl_add_u64 v[190:191], v[190:191], 0, v[210:211]
	s_mov_b32 vcc_lo, 0x0ff00ff0
	s_mov_b32 vcc_hi, 0x0ff00ff0
	v_mov_b32_e32 v210, v122
	v_cndmask_b32_e32 v122, v122, v124, vcc
	v_cndmask_b32_e32 v124, v124, v210, vcc
	v_mov_b32_e32 v210, v123
	v_cndmask_b32_e32 v123, v123, v125, vcc
	v_cndmask_b32_e32 v125, v125, v210, vcc
	global_store_dwordx2 v[190:191], v[122:123], off
	global_store_dwordx2 v[190:191], v[124:125], off offset:16

.LBB0_267:
	s_andn2_b64 vcc, exec, s[2:3]
	s_cbranch_vccnz .LBB0_269
	v_lshlrev_b32_e32 v210, 1, v140
	v_lshl_add_u64 v[122:123], v[122:123], 0, v[210:211]
	v_lshlrev_b32_e32 v210, 1, v142
	v_lshl_add_u64 v[122:123], v[122:123], 0, v[210:211]
	s_mov_b32 vcc_lo, 0x0ff00ff0
	s_mov_b32 vcc_hi, 0x0ff00ff0
	v_mov_b32_e32 v210, v114
	v_cndmask_b32_e32 v114, v114, v116, vcc
	v_cndmask_b32_e32 v116, v116, v210, vcc
	v_mov_b32_e32 v210, v115
	v_cndmask_b32_e32 v115, v115, v117, vcc
	v_cndmask_b32_e32 v117, v117, v210, vcc
	global_store_dwordx2 v[122:123], v[114:115], off
	global_store_dwordx2 v[122:123], v[116:117], off offset:16

.LBB0_280:
	s_andn2_b64 vcc, exec, s[2:3]
	s_cbranch_vccnz .LBB0_282
	v_lshlrev_b32_e32 v210, 1, v140
	v_lshl_add_u64 v[102:103], v[102:103], 0, v[210:211]
	v_lshlrev_b32_e32 v210, 1, v142
	v_lshl_add_u64 v[102:103], v[102:103], 0, v[210:211]
	s_mov_b32 vcc_lo, 0x0ff00ff0
	s_mov_b32 vcc_hi, 0x0ff00ff0
	v_mov_b32_e32 v210, v98
	v_cndmask_b32_e32 v98, v98, v100, vcc
	v_cndmask_b32_e32 v100, v100, v210, vcc
	v_mov_b32_e32 v210, v99
	v_cndmask_b32_e32 v99, v99, v101, vcc
	v_cndmask_b32_e32 v101, v101, v210, vcc
	global_store_dwordx2 v[102:103], v[98:99], off
	global_store_dwordx2 v[102:103], v[100:101], off offset:16

.LBB0_293:
	s_andn2_b64 vcc, exec, s[2:3]
	s_cbranch_vccnz .LBB0_295
	v_lshlrev_b32_e32 v210, 1, v140
	v_lshl_add_u64 v[86:87], v[86:87], 0, v[210:211]
	v_lshlrev_b32_e32 v210, 1, v142
	v_lshl_add_u64 v[86:87], v[86:87], 0, v[210:211]
	s_mov_b32 vcc_lo, 0x0ff00ff0
	s_mov_b32 vcc_hi, 0x0ff00ff0
	v_mov_b32_e32 v210, v82
	v_cndmask_b32_e32 v82, v82, v84, vcc
	v_cndmask_b32_e32 v84, v84, v210, vcc
	v_mov_b32_e32 v210, v83
	v_cndmask_b32_e32 v83, v83, v85, vcc
	v_cndmask_b32_e32 v85, v85, v210, vcc
	global_store_dwordx2 v[86:87], v[82:83], off
	global_store_dwordx2 v[86:87], v[84:85], off offset:16

.LBB0_306:
	s_andn2_b64 vcc, exec, s[2:3]
	s_cbranch_vccnz .LBB0_308
	v_lshlrev_b32_e32 v210, 1, v140
	v_lshl_add_u64 v[70:71], v[70:71], 0, v[210:211]
	v_lshlrev_b32_e32 v210, 1, v142
	v_lshl_add_u64 v[70:71], v[70:71], 0, v[210:211]
	s_mov_b32 vcc_lo, 0x0ff00ff0
	s_mov_b32 vcc_hi, 0x0ff00ff0
	v_mov_b32_e32 v210, v66
	v_cndmask_b32_e32 v66, v66, v68, vcc
	v_cndmask_b32_e32 v68, v68, v210, vcc
	v_mov_b32_e32 v210, v67
	v_cndmask_b32_e32 v67, v67, v69, vcc
	v_cndmask_b32_e32 v69, v69, v210, vcc
	global_store_dwordx2 v[70:71], v[66:67], off
	global_store_dwordx2 v[70:71], v[68:69], off offset:16

.LBB0_319:
	s_andn2_b64 vcc, exec, s[2:3]
	s_cbranch_vccnz .LBB0_321
	v_lshlrev_b32_e32 v210, 1, v140
	v_lshl_add_u64 v[54:55], v[54:55], 0, v[210:211]
	v_lshlrev_b32_e32 v210, 1, v142
	v_lshl_add_u64 v[54:55], v[54:55], 0, v[210:211]
	s_mov_b32 vcc_lo, 0x0ff00ff0
	s_mov_b32 vcc_hi, 0x0ff00ff0
	v_mov_b32_e32 v210, v50
	v_cndmask_b32_e32 v50, v50, v52, vcc
	v_cndmask_b32_e32 v52, v52, v210, vcc
	v_mov_b32_e32 v210, v51
	v_cndmask_b32_e32 v51, v51, v53, vcc
	v_cndmask_b32_e32 v53, v53, v210, vcc
	global_store_dwordx2 v[54:55], v[50:51], off
	global_store_dwordx2 v[54:55], v[52:53], off offset:16

.LBB0_332:
	s_andn2_b64 vcc, exec, s[2:3]
	s_cbranch_vccnz .LBB0_334
	v_lshlrev_b32_e32 v210, 1, v140
	v_lshl_add_u64 v[38:39], v[38:39], 0, v[210:211]
	v_lshlrev_b32_e32 v210, 1, v142
	v_lshl_add_u64 v[38:39], v[38:39], 0, v[210:211]
	s_mov_b32 vcc_lo, 0x0ff00ff0
	s_mov_b32 vcc_hi, 0x0ff00ff0
	v_mov_b32_e32 v210, v34
	v_cndmask_b32_e32 v34, v34, v36, vcc
	v_cndmask_b32_e32 v36, v36, v210, vcc
	v_mov_b32_e32 v210, v35
	v_cndmask_b32_e32 v35, v35, v37, vcc
	v_cndmask_b32_e32 v37, v37, v210, vcc
	global_store_dwordx2 v[38:39], v[34:35], off
	global_store_dwordx2 v[38:39], v[36:37], off offset:16

.LBB0_345:
	s_andn2_b64 vcc, exec, s[2:3]
	s_cbranch_vccnz .LBB0_347
	v_lshlrev_b32_e32 v210, 1, v140
	v_lshl_add_u64 v[22:23], v[22:23], 0, v[210:211]
	v_lshlrev_b32_e32 v210, 1, v142
	v_lshl_add_u64 v[22:23], v[22:23], 0, v[210:211]
	s_mov_b32 vcc_lo, 0x0ff00ff0
	s_mov_b32 vcc_hi, 0x0ff00ff0
	v_mov_b32_e32 v210, v18
	v_cndmask_b32_e32 v18, v18, v20, vcc
	v_cndmask_b32_e32 v20, v20, v210, vcc
	v_mov_b32_e32 v210, v19
	v_cndmask_b32_e32 v19, v19, v21, vcc
	v_cndmask_b32_e32 v21, v21, v210, vcc
	global_store_dwordx2 v[22:23], v[18:19], off
	global_store_dwordx2 v[22:23], v[20:21], off offset:16

.LBB0_360:
	v_lshlrev_b32_e32 v210, 1, v140
	v_lshl_add_u64 v[110:111], v[110:111], 0, v[210:211]
	v_lshlrev_b32_e32 v210, 1, v142
	v_lshl_add_u64 v[110:111], v[110:111], 0, v[210:211]
	s_mov_b32 vcc_lo, 0x0ff00ff0
	s_mov_b32 vcc_hi, 0x0ff00ff0
	v_mov_b32_e32 v210, v106
	v_cndmask_b32_e32 v106, v106, v108, vcc
	v_cndmask_b32_e32 v108, v108, v210, vcc
	v_mov_b32_e32 v210, v107
	v_cndmask_b32_e32 v107, v107, v109, vcc
	v_cndmask_b32_e32 v109, v109, v210, vcc
	global_store_dwordx2 v[110:111], v[106:107], off
	global_store_dwordx2 v[110:111], v[108:109], off offset:16
	s_and_b64 vcc, exec, s[8:9]
	s_mov_b64 s[2:3], -1
	s_cbranch_vccnz .LBB0_276

.LBB0_363:
	v_lshlrev_b32_e32 v210, 1, v140
	v_lshl_add_u64 v[94:95], v[94:95], 0, v[210:211]
	v_lshlrev_b32_e32 v210, 1, v142
	v_lshl_add_u64 v[94:95], v[94:95], 0, v[210:211]
	s_mov_b32 vcc_lo, 0x0ff00ff0
	s_mov_b32 vcc_hi, 0x0ff00ff0
	v_mov_b32_e32 v210, v90
	v_cndmask_b32_e32 v90, v90, v92, vcc
	v_cndmask_b32_e32 v92, v92, v210, vcc
	v_mov_b32_e32 v210, v91
	v_cndmask_b32_e32 v91, v91, v93, vcc
	v_cndmask_b32_e32 v93, v93, v210, vcc
	global_store_dwordx2 v[94:95], v[90:91], off
	global_store_dwordx2 v[94:95], v[92:93], off offset:16
	s_and_b64 vcc, exec, s[8:9]
	s_mov_b64 s[2:3], -1
	s_cbranch_vccnz .LBB0_289

.LBB0_366:
	v_lshlrev_b32_e32 v210, 1, v140
	v_lshl_add_u64 v[78:79], v[78:79], 0, v[210:211]
	v_lshlrev_b32_e32 v210, 1, v142
	v_lshl_add_u64 v[78:79], v[78:79], 0, v[210:211]
	s_mov_b32 vcc_lo, 0x0ff00ff0
	s_mov_b32 vcc_hi, 0x0ff00ff0
	v_mov_b32_e32 v210, v74
	v_cndmask_b32_e32 v74, v74, v76, vcc
	v_cndmask_b32_e32 v76, v76, v210, vcc
	v_mov_b32_e32 v210, v75
	v_cndmask_b32_e32 v75, v75, v77, vcc
	v_cndmask_b32_e32 v77, v77, v210, vcc
	global_store_dwordx2 v[78:79], v[74:75], off
	global_store_dwordx2 v[78:79], v[76:77], off offset:16
	s_and_b64 vcc, exec, s[8:9]
	s_mov_b64 s[2:3], -1
	s_cbranch_vccnz .LBB0_302

.LBB0_369:
	v_lshlrev_b32_e32 v210, 1, v140
	v_lshl_add_u64 v[62:63], v[62:63], 0, v[210:211]
	v_lshlrev_b32_e32 v210, 1, v142
	v_lshl_add_u64 v[62:63], v[62:63], 0, v[210:211]
	s_mov_b32 vcc_lo, 0x0ff00ff0
	s_mov_b32 vcc_hi, 0x0ff00ff0
	v_mov_b32_e32 v210, v58
	v_cndmask_b32_e32 v58, v58, v60, vcc
	v_cndmask_b32_e32 v60, v60, v210, vcc
	v_mov_b32_e32 v210, v59
	v_cndmask_b32_e32 v59, v59, v61, vcc
	v_cndmask_b32_e32 v61, v61, v210, vcc
	global_store_dwordx2 v[62:63], v[58:59], off
	global_store_dwordx2 v[62:63], v[60:61], off offset:16
	s_and_b64 vcc, exec, s[8:9]
	s_mov_b64 s[2:3], -1
	s_cbranch_vccnz .LBB0_315

.LBB0_372:
	v_lshlrev_b32_e32 v210, 1, v140
	v_lshl_add_u64 v[46:47], v[46:47], 0, v[210:211]
	v_lshlrev_b32_e32 v210, 1, v142
	v_lshl_add_u64 v[46:47], v[46:47], 0, v[210:211]
	s_mov_b32 vcc_lo, 0x0ff00ff0
	s_mov_b32 vcc_hi, 0x0ff00ff0
	v_mov_b32_e32 v210, v42
	v_cndmask_b32_e32 v42, v42, v44, vcc
	v_cndmask_b32_e32 v44, v44, v210, vcc
	v_mov_b32_e32 v210, v43
	v_cndmask_b32_e32 v43, v43, v45, vcc
	v_cndmask_b32_e32 v45, v45, v210, vcc
	global_store_dwordx2 v[46:47], v[42:43], off
	global_store_dwordx2 v[46:47], v[44:45], off offset:16
	s_and_b64 vcc, exec, s[8:9]
	s_mov_b64 s[2:3], -1
	s_cbranch_vccnz .LBB0_328

.LBB0_375:
	v_lshlrev_b32_e32 v210, 1, v140
	v_lshl_add_u64 v[30:31], v[30:31], 0, v[210:211]
	v_lshlrev_b32_e32 v210, 1, v142
	v_lshl_add_u64 v[30:31], v[30:31], 0, v[210:211]
	s_mov_b32 vcc_lo, 0x0ff00ff0
	s_mov_b32 vcc_hi, 0x0ff00ff0
	v_mov_b32_e32 v210, v26
	v_cndmask_b32_e32 v26, v26, v28, vcc
	v_cndmask_b32_e32 v28, v28, v210, vcc
	v_mov_b32_e32 v210, v27
	v_cndmask_b32_e32 v27, v27, v29, vcc
	v_cndmask_b32_e32 v29, v29, v210, vcc
	global_store_dwordx2 v[30:31], v[26:27], off
	global_store_dwordx2 v[30:31], v[28:29], off offset:16
	s_and_b64 vcc, exec, s[8:9]
	s_mov_b64 s[2:3], -1
	s_cbranch_vccnz .LBB0_341

.LBB0_378:
	v_lshlrev_b32_e32 v210, 1, v140
	v_lshl_add_u64 v[14:15], v[14:15], 0, v[210:211]
	v_lshlrev_b32_e32 v210, 1, v142
	v_lshl_add_u64 v[14:15], v[14:15], 0, v[210:211]
	s_mov_b32 vcc_lo, 0x0ff00ff0
	s_mov_b32 vcc_hi, 0x0ff00ff0
	v_mov_b32_e32 v210, v10
	v_cndmask_b32_e32 v10, v10, v12, vcc
	v_cndmask_b32_e32 v12, v12, v210, vcc
	v_mov_b32_e32 v210, v11
	v_cndmask_b32_e32 v11, v11, v13, vcc
	v_cndmask_b32_e32 v13, v13, v210, vcc
	global_store_dwordx2 v[14:15], v[10:11], off
	global_store_dwordx2 v[14:15], v[12:13], off offset:16
	s_and_b64 vcc, exec, s[8:9]
	s_mov_b64 s[2:3], -1
	s_cbranch_vccnz .LBB0_354

.LBB0_381:
	v_lshlrev_b32_e32 v210, 1, v140
	v_lshl_add_u64 v[6:7], v[6:7], 0, v[210:211]
	v_lshlrev_b32_e32 v210, 1, v142
	v_lshl_add_u64 v[6:7], v[6:7], 0, v[210:211]
	s_mov_b32 vcc_lo, 0x0ff00ff0
	s_mov_b32 vcc_hi, 0x0ff00ff0
	v_mov_b32_e32 v210, v2
	v_cndmask_b32_e32 v2, v2, v4, vcc
	v_cndmask_b32_e32 v4, v4, v210, vcc
	v_mov_b32_e32 v210, v3
	v_cndmask_b32_e32 v3, v3, v5, vcc
	v_cndmask_b32_e32 v5, v5, v210, vcc
	global_store_dwordx2 v[6:7], v[2:3], off
	global_store_dwordx2 v[6:7], v[4:5], off offset:16
	s_andn2_b64 vcc, exec, s[6:7]
	s_mov_b64 s[2:3], -1
	s_cbranch_vccnz .LBB0_218

.LBB0_682:
	v_readlane_b32 s2, v253, 55
	s_waitcnt lgkmcnt(0)
	s_barrier
	v_mov_b32_e32 v2, s2
	ds_read_b32 v2, v2
	v_readlane_b32 s2, v253, 26
	v_readlane_b32 s3, v253, 27
	s_lshl_b32 s52, s29, 5
	s_andn2_b64 vcc, exec, s[2:3]
	s_waitcnt lgkmcnt(0)
	v_readfirstlane_b32 s53, v2
	v_readfirstlane_b32 s2, v1
	s_cbranch_vccnz .LBB0_748
	v_writelane_b32 v254, s6, 59
	v_sub_f32_e64 v193, 1.0, s2
	s_add_u32 s2, s40, 0x1a400000
	v_writelane_b32 v254, s7, 60
	v_writelane_b32 v254, s2, 61
	s_addc_u32 s2, s41, 0
	s_lshl_b32 s74, s44, 8
	v_writelane_b32 v254, s2, 62
	s_lshl_b64 s[2:3], s[74:75], 2
	s_add_u32 s4, s0, s2
	s_addc_u32 s5, s1, s3
	s_ashr_i32 s2, s29, 2
	s_lshl_b32 s0, s2, 7
	s_ashr_i32 s1, s0, 31
	s_and_b32 s3, s29, 3
	s_bfe_u32 s62, s29, 0x10001
	s_lshl_b64 s[0:1], s[0:1], 1
	s_add_u32 s0, s40, s0
	s_addc_u32 s1, s41, s1
	s_cmpk_lt_i32 s29, 0x46
	s_cselect_b64 s[54:55], -1, 0
	s_lshl_b32 s80, s29, 10
	s_add_i32 s63, s80, 0
	s_ashr_i32 s81, s80, 31
	s_cmp_lt_i32 s29, 62
	s_cselect_b64 s[88:89], -1, 0
	s_add_i32 s92, s80, 0x2000
	s_ashr_i32 s93, s92, 31
	s_cmp_lt_i32 s29, 54
	s_cselect_b64 s[96:97], -1, 0
	s_add_i32 s24, s80, 0x4000
	s_ashr_i32 s25, s24, 31
	v_ashrrev_i32_e32 v2, 1, v192
	s_cmp_lt_i32 s29, 46
	v_and_b32_e32 v2, -8, v2
	s_cselect_b64 s[86:87], -1, 0
	s_add_i32 s84, s80, 0x6000
	v_ashrrev_i32_e32 v3, 31, v2
	s_ashr_i32 s85, s84, 31
	v_lshl_add_u64 v[2:3], v[2:3], 1, s[0:1]
	s_mov_b64 s[0:1], 0xa400000
	v_lshlrev_b32_e32 v210, 4, v192
	s_cmp_lt_i32 s29, 38
	v_lshl_add_u64 v[194:195], v[2:3], 0, s[0:1]
	v_lshl_add_u64 v[2:3], s[40:41], 0, v[210:211]
	s_cselect_b64 s[40:41], -1, 0
	s_add_i32 s94, s80, 0x8000
	s_ashr_i32 s95, s94, 31
	s_cmp_lt_i32 s29, 30
	s_cselect_b64 s[46:47], -1, 0
	s_add_i32 s48, s80, 0xa000
	s_ashr_i32 s49, s48, 31
	s_cmp_lt_i32 s29, 22
	s_cselect_b64 s[36:37], -1, 0
	s_add_i32 s56, s80, 0xc000
	s_ashr_i32 s57, s56, 31
	s_cmp_lt_i32 s29, 14
	s_cselect_b64 s[30:31], -1, 0
	s_add_i32 s66, s80, 0xe000
	s_ashr_i32 s67, s66, 31
	s_cmp_lt_i32 s29, 6
	s_cselect_b64 s[90:91], -1, 0
	s_add_i32 s38, s80, 0x10000
	s_lshl_b32 s0, s3, 15
	v_lshl_add_u64 v[196:197], v[2:3], 0, s[70:71]
	s_add_i32 s68, s63, 0x10000
	s_ashr_i32 s39, s38, 31
	s_add_i32 s70, s0, 0
	v_writelane_b32 v254, s44, 63
	s_cmp_eq_u32 s2, 1
	v_and_b32_e32 v1, 15, v192
	s_cselect_b64 s[26:27], -1, 0
	s_cmp_lt_u32 s29, 4
	v_readlane_b32 s0, v254, 22
	v_lshl_or_b32 v224, s3, 5, v1
	s_mul_i32 s69, s2, 0x4400
	v_mul_u32_u24_e32 v210, 0x110, v1
	v_add_u32_e32 v225, 4, v192
	v_and_b32_e32 v225, 8, v225
	v_lshlrev_b32_e32 v225, 1, v225
	v_xor_b32_e32 v225, v192, v225
	v_and_b32_e32 v225, -16, v225
	v_mul_u32_u24_e32 v226, 0x90, v1
	v_writelane_b32 v255, s29, 0
	s_cselect_b64 s[82:83], -1, 0
	s_mov_b32 s71, s0
	v_readlane_b32 s1, v254, 23
	s_branch .LBB0_685
